# P0 adaLN partials: 16 weight rows loaded up front, silu(cvec) computed once per wave (two per lane) and broadcast by v_readlane; same op sequence and accumulation order
# speedup vs baseline: 1.0396x; 1.0083x over previous
; DI float silu_f(float x) { return x * __builtin_amdgcn_rcpf(1.f + __expf(-x)); }
; DI void phase0(const float* cvec, const float* ada_w, const float* w_in, const float* w_out, bf16* WIN, bf16* WOUT, float* MODP, float* KMAX, bf16* WDT,
;                LAS unsigned char* lds, int tid, int G) {
;     ...
;     for (int task = blockIdx.x; task < 192; task += G) {
;         const int l = task / 96, rem = task % 96, cgp = rem >> 3, ks = rem & 7;
;         const float* W = ada_w + (size_t)l * 1024 * 3072;
;         const int k0 = ks * 128 + wave * 16, col = cgp * 256 + lane * 4;
;         f32x4 acc[8];
; #pragma unroll
;         for (int b = 0; b < 8; ++b) acc[b] = (f32x4){0.f, 0.f, 0.f, 0.f};
; #pragma unroll 4
;         for (int kk = 0; kk < 16; ++kk) { const int k = k0 + kk; const f32x4 w = __builtin_nontemporal_load((const f32x4*)(W + (size_t)k * 3072 + col));
; #pragma unroll
;             for (int b = 0; b < 8; ++b) { const float ca = silu_f(cvec[b * 1024 + k]); acc[b] += w * ca; } }
.LBB0_40:
	s_mul_hi_i32 s8, s20, 0x2aaaaaab
	s_lshr_b32 s9, s8, 31
	s_ashr_i32 s8, s8, 4
	s_add_i32 s9, s8, s9
	s_mul_i32 s8, s9, 0x60
	s_sub_i32 s8, s20, s8
	s_and_b32 s21, s8, 7
	s_lshl_b32 s8, s8, 5
	s_and_b32 s8, s8, 0xffffff00
	v_lshl_add_u32 v0, s21, 7, v53
	v_mad_i64_i32 v[2:3], s[10:11], v0, s12, 0
	v_or_b32_e32 v4, s8, v52
	v_mad_i64_i32 v[2:3], s[10:11], s9, v56, v[2:3]
	v_ashrrev_i32_e32 v5, 31, v4
	v_ashrrev_i32_e32 v1, 31, v0
	v_lshl_add_u64 v[2:3], v[4:5], 2, v[2:3]
	v_lshl_add_u64 v[40:41], s[4:5], 0, v[2:3]
	v_lshl_add_u64 v[42:43], v[0:1], 2, s[38:39]
	s_mov_b64 s[10:11], 0
	v_mov_b32_e32 v0, 0
	v_mov_b32_e32 v1, v39
	v_mov_b32_e32 v2, 0
	v_mov_b32_e32 v3, v39
	v_mov_b32_e32 v28, 0
	v_mov_b32_e32 v29, v39
	v_mov_b32_e32 v30, 0
	v_mov_b32_e32 v31, v39
	v_mov_b32_e32 v4, 0
	v_mov_b32_e32 v5, v39
	v_mov_b32_e32 v6, 0
	v_mov_b32_e32 v7, v39
	v_mov_b32_e32 v8, 0
	v_mov_b32_e32 v9, v39
	v_mov_b32_e32 v10, 0
	v_mov_b32_e32 v11, v39
	v_mov_b32_e32 v12, 0
	v_mov_b32_e32 v13, v39
	v_mov_b32_e32 v14, 0
	v_mov_b32_e32 v15, v39
	v_mov_b32_e32 v16, 0
	v_mov_b32_e32 v17, v39
	v_mov_b32_e32 v18, 0
	v_mov_b32_e32 v19, v39
	v_mov_b32_e32 v20, 0
	v_mov_b32_e32 v21, v39
	v_mov_b32_e32 v22, 0
	v_mov_b32_e32 v23, v39
	v_mov_b32_e32 v24, 0
	v_mov_b32_e32 v25, v39
	v_mov_b32_e32 v26, 0
	v_mov_b32_e32 v27, v39
	v_mbcnt_lo_u32_b32 v44, -1, 0
	v_mbcnt_hi_u32_b32 v44, -1, v44
	v_lshrrev_b32_e32 v45, 4, v44
	v_and_b32_e32 v44, 15, v44
	v_lshl_add_u32 v44, v45, 10, v44
	v_lshlrev_b32_e32 v44, 2, v44
	v_mov_b32_e32 v45, 0
	v_lshl_add_u64 v[44:45], v[42:43], 0, v[44:45]
	v_add_co_u32_e32 v46, vcc, s15, v44
	s_nop 1
	v_addc_co_u32_e32 v47, vcc, 0, v45, vcc
	global_load_dword v48, v[44:45], off
	global_load_dword v49, v[46:47], off
	v_add_co_u32_e32 v50, vcc, s13, v40
	s_nop 1
	v_addc_co_u32_e32 v51, vcc, -1, v41, vcc
	v_add_co_u32_e32 v122, vcc, s18, v40
	s_nop 1
	v_addc_co_u32_e32 v123, vcc, -1, v41, vcc
	v_add_co_u32_e32 v124, vcc, s19, v40
	s_nop 1
	v_addc_co_u32_e32 v125, vcc, -1, v41, vcc
	global_load_dwordx4 v[58:61], v[50:51], off nt
	global_load_dwordx4 v[62:65], v[122:123], off nt
	global_load_dwordx4 v[66:69], v[124:125], off nt
	global_load_dwordx4 v[70:73], v[40:41], off nt
	v_lshl_add_u64 v[50:51], v[50:51], 0, s[6:7]
	v_lshl_add_u64 v[122:123], v[122:123], 0, s[6:7]
	v_lshl_add_u64 v[124:125], v[124:125], 0, s[6:7]
	v_lshl_add_u64 v[40:41], v[40:41], 0, s[6:7]
	global_load_dwordx4 v[74:77], v[50:51], off nt
	global_load_dwordx4 v[78:81], v[122:123], off nt
	global_load_dwordx4 v[82:85], v[124:125], off nt
	global_load_dwordx4 v[86:89], v[40:41], off nt
	v_lshl_add_u64 v[50:51], v[50:51], 0, s[6:7]
	v_lshl_add_u64 v[122:123], v[122:123], 0, s[6:7]
	v_lshl_add_u64 v[124:125], v[124:125], 0, s[6:7]
	v_lshl_add_u64 v[40:41], v[40:41], 0, s[6:7]
	global_load_dwordx4 v[90:93], v[50:51], off nt
	global_load_dwordx4 v[94:97], v[122:123], off nt
	global_load_dwordx4 v[98:101], v[124:125], off nt
	global_load_dwordx4 v[102:105], v[40:41], off nt
	v_lshl_add_u64 v[50:51], v[50:51], 0, s[6:7]
	v_lshl_add_u64 v[122:123], v[122:123], 0, s[6:7]
	v_lshl_add_u64 v[124:125], v[124:125], 0, s[6:7]
	v_lshl_add_u64 v[40:41], v[40:41], 0, s[6:7]
	global_load_dwordx4 v[106:109], v[50:51], off nt
	global_load_dwordx4 v[110:113], v[122:123], off nt
	global_load_dwordx4 v[114:117], v[124:125], off nt
	global_load_dwordx4 v[118:121], v[40:41], off nt
	s_waitcnt vmcnt(16)
	v_mul_f32_e32 v44, 0xbfb8aa3b, v48
	v_mul_f32_e32 v45, 0xbfb8aa3b, v49
	v_exp_f32_e32 v44, v44
	v_exp_f32_e32 v45, v45
	s_nop 0
	v_add_f32_e32 v44, 1.0, v44
	v_add_f32_e32 v45, 1.0, v45
	v_rcp_f32_e32 v44, v44
	v_rcp_f32_e32 v45, v45
	s_nop 0
	v_mul_f32_e32 v48, v48, v44
	v_mul_f32_e32 v49, v49, v45
	s_waitcnt vmcnt(15)
	v_readlane_b32 s22, v48, 0
	v_readlane_b32 s24, v48, 16
	v_readlane_b32 s26, v48, 32
	v_readlane_b32 s28, v48, 48
	v_readlane_b32 s30, v49, 0
	v_readlane_b32 s52, v49, 16
	v_readlane_b32 s54, v49, 32
	v_readlane_b32 s56, v49, 48
	v_pk_fma_f32 v[28:29], v[58:59], s[22:23], v[28:29] op_sel_hi:[1,0,1]
	v_pk_fma_f32 v[30:31], v[60:61], s[22:23], v[30:31] op_sel_hi:[1,0,1]
	v_pk_fma_f32 v[4:5], v[58:59], s[24:25], v[4:5] op_sel_hi:[1,0,1]
	v_pk_fma_f32 v[6:7], v[60:61], s[24:25], v[6:7] op_sel_hi:[1,0,1]
	v_pk_fma_f32 v[8:9], v[58:59], s[26:27], v[8:9] op_sel_hi:[1,0,1]
	v_pk_fma_f32 v[10:11], v[60:61], s[26:27], v[10:11] op_sel_hi:[1,0,1]
	v_pk_fma_f32 v[12:13], v[58:59], s[28:29], v[12:13] op_sel_hi:[1,0,1]
	v_pk_fma_f32 v[14:15], v[60:61], s[28:29], v[14:15] op_sel_hi:[1,0,1]
	v_pk_fma_f32 v[16:17], v[58:59], s[30:31], v[16:17] op_sel_hi:[1,0,1]
	v_pk_fma_f32 v[18:19], v[60:61], s[30:31], v[18:19] op_sel_hi:[1,0,1]
	v_pk_fma_f32 v[20:21], v[58:59], s[52:53], v[20:21] op_sel_hi:[1,0,1]
	v_pk_fma_f32 v[22:23], v[60:61], s[52:53], v[22:23] op_sel_hi:[1,0,1]
	v_pk_fma_f32 v[24:25], v[58:59], s[54:55], v[24:25] op_sel_hi:[1,0,1]
	v_pk_fma_f32 v[26:27], v[60:61], s[54:55], v[26:27] op_sel_hi:[1,0,1]
	v_pk_fma_f32 v[0:1], v[58:59], s[56:57], v[0:1] op_sel_hi:[1,0,1]
	v_pk_fma_f32 v[2:3], v[60:61], s[56:57], v[2:3] op_sel_hi:[1,0,1]
	s_waitcnt vmcnt(14)
; DI float silu_f(float x) { return x * __builtin_amdgcn_rcpf(1.f + __expf(-x)); }
; DI void phase0(const float* cvec, const float* ada_w, const float* w_in, const float* w_out, bf16* WIN, bf16* WOUT, float* MODP, float* KMAX, bf16* WDT,
;                LAS unsigned char* lds, int tid, int G) {
;     ...
; #pragma unroll 4
;         for (int kk = 0; kk < 16; ++kk) { const int k = k0 + kk; const f32x4 w = __builtin_nontemporal_load((const f32x4*)(W + (size_t)k * 3072 + col));
; #pragma unroll
;             for (int b = 0; b < 8; ++b) { const float ca = silu_f(cvec[b * 1024 + k]); acc[b] += w * ca; } }
	v_readlane_b32 s22, v48, 1
	v_readlane_b32 s24, v48, 17
	v_readlane_b32 s26, v48, 33
	v_readlane_b32 s28, v48, 49
	v_readlane_b32 s30, v49, 1
	v_readlane_b32 s52, v49, 17
	v_readlane_b32 s54, v49, 33
	v_readlane_b32 s56, v49, 49
	v_pk_fma_f32 v[28:29], v[62:63], s[22:23], v[28:29] op_sel_hi:[1,0,1]
	v_pk_fma_f32 v[30:31], v[64:65], s[22:23], v[30:31] op_sel_hi:[1,0,1]
	v_pk_fma_f32 v[4:5], v[62:63], s[24:25], v[4:5] op_sel_hi:[1,0,1]
	v_pk_fma_f32 v[6:7], v[64:65], s[24:25], v[6:7] op_sel_hi:[1,0,1]
	v_pk_fma_f32 v[8:9], v[62:63], s[26:27], v[8:9] op_sel_hi:[1,0,1]
	v_pk_fma_f32 v[10:11], v[64:65], s[26:27], v[10:11] op_sel_hi:[1,0,1]
	v_pk_fma_f32 v[12:13], v[62:63], s[28:29], v[12:13] op_sel_hi:[1,0,1]
	v_pk_fma_f32 v[14:15], v[64:65], s[28:29], v[14:15] op_sel_hi:[1,0,1]
	v_pk_fma_f32 v[16:17], v[62:63], s[30:31], v[16:17] op_sel_hi:[1,0,1]
	v_pk_fma_f32 v[18:19], v[64:65], s[30:31], v[18:19] op_sel_hi:[1,0,1]
	v_pk_fma_f32 v[20:21], v[62:63], s[52:53], v[20:21] op_sel_hi:[1,0,1]
	v_pk_fma_f32 v[22:23], v[64:65], s[52:53], v[22:23] op_sel_hi:[1,0,1]
	v_pk_fma_f32 v[24:25], v[62:63], s[54:55], v[24:25] op_sel_hi:[1,0,1]
	v_pk_fma_f32 v[26:27], v[64:65], s[54:55], v[26:27] op_sel_hi:[1,0,1]
	v_pk_fma_f32 v[0:1], v[62:63], s[56:57], v[0:1] op_sel_hi:[1,0,1]
	v_pk_fma_f32 v[2:3], v[64:65], s[56:57], v[2:3] op_sel_hi:[1,0,1]
	s_waitcnt vmcnt(13)
	v_readlane_b32 s22, v48, 2
	v_readlane_b32 s24, v48, 18
	v_readlane_b32 s26, v48, 34
	v_readlane_b32 s28, v48, 50
	v_readlane_b32 s30, v49, 2
	v_readlane_b32 s52, v49, 18
	v_readlane_b32 s54, v49, 34
	v_readlane_b32 s56, v49, 50
	v_pk_fma_f32 v[28:29], v[66:67], s[22:23], v[28:29] op_sel_hi:[1,0,1]
	v_pk_fma_f32 v[30:31], v[68:69], s[22:23], v[30:31] op_sel_hi:[1,0,1]
	v_pk_fma_f32 v[4:5], v[66:67], s[24:25], v[4:5] op_sel_hi:[1,0,1]
	v_pk_fma_f32 v[6:7], v[68:69], s[24:25], v[6:7] op_sel_hi:[1,0,1]
	v_pk_fma_f32 v[8:9], v[66:67], s[26:27], v[8:9] op_sel_hi:[1,0,1]
	v_pk_fma_f32 v[10:11], v[68:69], s[26:27], v[10:11] op_sel_hi:[1,0,1]
	v_pk_fma_f32 v[12:13], v[66:67], s[28:29], v[12:13] op_sel_hi:[1,0,1]
	v_pk_fma_f32 v[14:15], v[68:69], s[28:29], v[14:15] op_sel_hi:[1,0,1]
	v_pk_fma_f32 v[16:17], v[66:67], s[30:31], v[16:17] op_sel_hi:[1,0,1]
	v_pk_fma_f32 v[18:19], v[68:69], s[30:31], v[18:19] op_sel_hi:[1,0,1]
	v_pk_fma_f32 v[20:21], v[66:67], s[52:53], v[20:21] op_sel_hi:[1,0,1]
	v_pk_fma_f32 v[22:23], v[68:69], s[52:53], v[22:23] op_sel_hi:[1,0,1]
	v_pk_fma_f32 v[24:25], v[66:67], s[54:55], v[24:25] op_sel_hi:[1,0,1]
	v_pk_fma_f32 v[26:27], v[68:69], s[54:55], v[26:27] op_sel_hi:[1,0,1]
	v_pk_fma_f32 v[0:1], v[66:67], s[56:57], v[0:1] op_sel_hi:[1,0,1]
	v_pk_fma_f32 v[2:3], v[68:69], s[56:57], v[2:3] op_sel_hi:[1,0,1]
	s_waitcnt vmcnt(12)
	v_readlane_b32 s22, v48, 3
	v_readlane_b32 s24, v48, 19
	v_readlane_b32 s26, v48, 35
	v_readlane_b32 s28, v48, 51
	v_readlane_b32 s30, v49, 3
	v_readlane_b32 s52, v49, 19
	v_readlane_b32 s54, v49, 35
	v_readlane_b32 s56, v49, 51
	v_pk_fma_f32 v[28:29], v[70:71], s[22:23], v[28:29] op_sel_hi:[1,0,1]
	v_pk_fma_f32 v[30:31], v[72:73], s[22:23], v[30:31] op_sel_hi:[1,0,1]
	v_pk_fma_f32 v[4:5], v[70:71], s[24:25], v[4:5] op_sel_hi:[1,0,1]
	v_pk_fma_f32 v[6:7], v[72:73], s[24:25], v[6:7] op_sel_hi:[1,0,1]
	v_pk_fma_f32 v[8:9], v[70:71], s[26:27], v[8:9] op_sel_hi:[1,0,1]
	v_pk_fma_f32 v[10:11], v[72:73], s[26:27], v[10:11] op_sel_hi:[1,0,1]
	v_pk_fma_f32 v[12:13], v[70:71], s[28:29], v[12:13] op_sel_hi:[1,0,1]
	v_pk_fma_f32 v[14:15], v[72:73], s[28:29], v[14:15] op_sel_hi:[1,0,1]
	v_pk_fma_f32 v[16:17], v[70:71], s[30:31], v[16:17] op_sel_hi:[1,0,1]
	v_pk_fma_f32 v[18:19], v[72:73], s[30:31], v[18:19] op_sel_hi:[1,0,1]
	v_pk_fma_f32 v[20:21], v[70:71], s[52:53], v[20:21] op_sel_hi:[1,0,1]
	v_pk_fma_f32 v[22:23], v[72:73], s[52:53], v[22:23] op_sel_hi:[1,0,1]
	v_pk_fma_f32 v[24:25], v[70:71], s[54:55], v[24:25] op_sel_hi:[1,0,1]
	v_pk_fma_f32 v[26:27], v[72:73], s[54:55], v[26:27] op_sel_hi:[1,0,1]
	v_pk_fma_f32 v[0:1], v[70:71], s[56:57], v[0:1] op_sel_hi:[1,0,1]
	v_pk_fma_f32 v[2:3], v[72:73], s[56:57], v[2:3] op_sel_hi:[1,0,1]
	s_waitcnt vmcnt(11)
	v_readlane_b32 s22, v48, 4
	v_readlane_b32 s24, v48, 20
	v_readlane_b32 s26, v48, 36
	v_readlane_b32 s28, v48, 52
	v_readlane_b32 s30, v49, 4
	v_readlane_b32 s52, v49, 20
	v_readlane_b32 s54, v49, 36
	v_readlane_b32 s56, v49, 52
	v_pk_fma_f32 v[28:29], v[74:75], s[22:23], v[28:29] op_sel_hi:[1,0,1]
	v_pk_fma_f32 v[30:31], v[76:77], s[22:23], v[30:31] op_sel_hi:[1,0,1]
	v_pk_fma_f32 v[4:5], v[74:75], s[24:25], v[4:5] op_sel_hi:[1,0,1]
	v_pk_fma_f32 v[6:7], v[76:77], s[24:25], v[6:7] op_sel_hi:[1,0,1]
	v_pk_fma_f32 v[8:9], v[74:75], s[26:27], v[8:9] op_sel_hi:[1,0,1]
	v_pk_fma_f32 v[10:11], v[76:77], s[26:27], v[10:11] op_sel_hi:[1,0,1]
	v_pk_fma_f32 v[12:13], v[74:75], s[28:29], v[12:13] op_sel_hi:[1,0,1]
	v_pk_fma_f32 v[14:15], v[76:77], s[28:29], v[14:15] op_sel_hi:[1,0,1]
	v_pk_fma_f32 v[16:17], v[74:75], s[30:31], v[16:17] op_sel_hi:[1,0,1]
	v_pk_fma_f32 v[18:19], v[76:77], s[30:31], v[18:19] op_sel_hi:[1,0,1]
	v_pk_fma_f32 v[20:21], v[74:75], s[52:53], v[20:21] op_sel_hi:[1,0,1]
	v_pk_fma_f32 v[22:23], v[76:77], s[52:53], v[22:23] op_sel_hi:[1,0,1]
	v_pk_fma_f32 v[24:25], v[74:75], s[54:55], v[24:25] op_sel_hi:[1,0,1]
	v_pk_fma_f32 v[26:27], v[76:77], s[54:55], v[26:27] op_sel_hi:[1,0,1]
	v_pk_fma_f32 v[0:1], v[74:75], s[56:57], v[0:1] op_sel_hi:[1,0,1]
	v_pk_fma_f32 v[2:3], v[76:77], s[56:57], v[2:3] op_sel_hi:[1,0,1]
	s_waitcnt vmcnt(10)
; DI float silu_f(float x) { return x * __builtin_amdgcn_rcpf(1.f + __expf(-x)); }
; DI void phase0(const float* cvec, const float* ada_w, const float* w_in, const float* w_out, bf16* WIN, bf16* WOUT, float* MODP, float* KMAX, bf16* WDT,
;                LAS unsigned char* lds, int tid, int G) {
;     ...
; #pragma unroll 4
;         for (int kk = 0; kk < 16; ++kk) { const int k = k0 + kk; const f32x4 w = __builtin_nontemporal_load((const f32x4*)(W + (size_t)k * 3072 + col));
; #pragma unroll
;             for (int b = 0; b < 8; ++b) { const float ca = silu_f(cvec[b * 1024 + k]); acc[b] += w * ca; } }
	v_readlane_b32 s22, v48, 5
	v_readlane_b32 s24, v48, 21
	v_readlane_b32 s26, v48, 37
	v_readlane_b32 s28, v48, 53
	v_readlane_b32 s30, v49, 5
	v_readlane_b32 s52, v49, 21
	v_readlane_b32 s54, v49, 37
	v_readlane_b32 s56, v49, 53
	v_pk_fma_f32 v[28:29], v[78:79], s[22:23], v[28:29] op_sel_hi:[1,0,1]
	v_pk_fma_f32 v[30:31], v[80:81], s[22:23], v[30:31] op_sel_hi:[1,0,1]
	v_pk_fma_f32 v[4:5], v[78:79], s[24:25], v[4:5] op_sel_hi:[1,0,1]
	v_pk_fma_f32 v[6:7], v[80:81], s[24:25], v[6:7] op_sel_hi:[1,0,1]
	v_pk_fma_f32 v[8:9], v[78:79], s[26:27], v[8:9] op_sel_hi:[1,0,1]
	v_pk_fma_f32 v[10:11], v[80:81], s[26:27], v[10:11] op_sel_hi:[1,0,1]
	v_pk_fma_f32 v[12:13], v[78:79], s[28:29], v[12:13] op_sel_hi:[1,0,1]
	v_pk_fma_f32 v[14:15], v[80:81], s[28:29], v[14:15] op_sel_hi:[1,0,1]
	v_pk_fma_f32 v[16:17], v[78:79], s[30:31], v[16:17] op_sel_hi:[1,0,1]
	v_pk_fma_f32 v[18:19], v[80:81], s[30:31], v[18:19] op_sel_hi:[1,0,1]
	v_pk_fma_f32 v[20:21], v[78:79], s[52:53], v[20:21] op_sel_hi:[1,0,1]
	v_pk_fma_f32 v[22:23], v[80:81], s[52:53], v[22:23] op_sel_hi:[1,0,1]
	v_pk_fma_f32 v[24:25], v[78:79], s[54:55], v[24:25] op_sel_hi:[1,0,1]
	v_pk_fma_f32 v[26:27], v[80:81], s[54:55], v[26:27] op_sel_hi:[1,0,1]
	v_pk_fma_f32 v[0:1], v[78:79], s[56:57], v[0:1] op_sel_hi:[1,0,1]
	v_pk_fma_f32 v[2:3], v[80:81], s[56:57], v[2:3] op_sel_hi:[1,0,1]
	s_waitcnt vmcnt(9)
	v_readlane_b32 s22, v48, 6
	v_readlane_b32 s24, v48, 22
	v_readlane_b32 s26, v48, 38
	v_readlane_b32 s28, v48, 54
	v_readlane_b32 s30, v49, 6
	v_readlane_b32 s52, v49, 22
	v_readlane_b32 s54, v49, 38
	v_readlane_b32 s56, v49, 54
	v_pk_fma_f32 v[28:29], v[82:83], s[22:23], v[28:29] op_sel_hi:[1,0,1]
	v_pk_fma_f32 v[30:31], v[84:85], s[22:23], v[30:31] op_sel_hi:[1,0,1]
	v_pk_fma_f32 v[4:5], v[82:83], s[24:25], v[4:5] op_sel_hi:[1,0,1]
	v_pk_fma_f32 v[6:7], v[84:85], s[24:25], v[6:7] op_sel_hi:[1,0,1]
	v_pk_fma_f32 v[8:9], v[82:83], s[26:27], v[8:9] op_sel_hi:[1,0,1]
	v_pk_fma_f32 v[10:11], v[84:85], s[26:27], v[10:11] op_sel_hi:[1,0,1]
	v_pk_fma_f32 v[12:13], v[82:83], s[28:29], v[12:13] op_sel_hi:[1,0,1]
	v_pk_fma_f32 v[14:15], v[84:85], s[28:29], v[14:15] op_sel_hi:[1,0,1]
	v_pk_fma_f32 v[16:17], v[82:83], s[30:31], v[16:17] op_sel_hi:[1,0,1]
	v_pk_fma_f32 v[18:19], v[84:85], s[30:31], v[18:19] op_sel_hi:[1,0,1]
	v_pk_fma_f32 v[20:21], v[82:83], s[52:53], v[20:21] op_sel_hi:[1,0,1]
	v_pk_fma_f32 v[22:23], v[84:85], s[52:53], v[22:23] op_sel_hi:[1,0,1]
	v_pk_fma_f32 v[24:25], v[82:83], s[54:55], v[24:25] op_sel_hi:[1,0,1]
	v_pk_fma_f32 v[26:27], v[84:85], s[54:55], v[26:27] op_sel_hi:[1,0,1]
	v_pk_fma_f32 v[0:1], v[82:83], s[56:57], v[0:1] op_sel_hi:[1,0,1]
	v_pk_fma_f32 v[2:3], v[84:85], s[56:57], v[2:3] op_sel_hi:[1,0,1]
	s_waitcnt vmcnt(8)
	v_readlane_b32 s22, v48, 7
	v_readlane_b32 s24, v48, 23
	v_readlane_b32 s26, v48, 39
	v_readlane_b32 s28, v48, 55
	v_readlane_b32 s30, v49, 7
	v_readlane_b32 s52, v49, 23
	v_readlane_b32 s54, v49, 39
	v_readlane_b32 s56, v49, 55
	v_pk_fma_f32 v[28:29], v[86:87], s[22:23], v[28:29] op_sel_hi:[1,0,1]
	v_pk_fma_f32 v[30:31], v[88:89], s[22:23], v[30:31] op_sel_hi:[1,0,1]
	v_pk_fma_f32 v[4:5], v[86:87], s[24:25], v[4:5] op_sel_hi:[1,0,1]
	v_pk_fma_f32 v[6:7], v[88:89], s[24:25], v[6:7] op_sel_hi:[1,0,1]
	v_pk_fma_f32 v[8:9], v[86:87], s[26:27], v[8:9] op_sel_hi:[1,0,1]
	v_pk_fma_f32 v[10:11], v[88:89], s[26:27], v[10:11] op_sel_hi:[1,0,1]
	v_pk_fma_f32 v[12:13], v[86:87], s[28:29], v[12:13] op_sel_hi:[1,0,1]
	v_pk_fma_f32 v[14:15], v[88:89], s[28:29], v[14:15] op_sel_hi:[1,0,1]
	v_pk_fma_f32 v[16:17], v[86:87], s[30:31], v[16:17] op_sel_hi:[1,0,1]
	v_pk_fma_f32 v[18:19], v[88:89], s[30:31], v[18:19] op_sel_hi:[1,0,1]
	v_pk_fma_f32 v[20:21], v[86:87], s[52:53], v[20:21] op_sel_hi:[1,0,1]
	v_pk_fma_f32 v[22:23], v[88:89], s[52:53], v[22:23] op_sel_hi:[1,0,1]
	v_pk_fma_f32 v[24:25], v[86:87], s[54:55], v[24:25] op_sel_hi:[1,0,1]
	v_pk_fma_f32 v[26:27], v[88:89], s[54:55], v[26:27] op_sel_hi:[1,0,1]
	v_pk_fma_f32 v[0:1], v[86:87], s[56:57], v[0:1] op_sel_hi:[1,0,1]
	v_pk_fma_f32 v[2:3], v[88:89], s[56:57], v[2:3] op_sel_hi:[1,0,1]
	s_waitcnt vmcnt(7)
	v_readlane_b32 s22, v48, 8
	v_readlane_b32 s24, v48, 24
	v_readlane_b32 s26, v48, 40
	v_readlane_b32 s28, v48, 56
	v_readlane_b32 s30, v49, 8
	v_readlane_b32 s52, v49, 24
	v_readlane_b32 s54, v49, 40
	v_readlane_b32 s56, v49, 56
	v_pk_fma_f32 v[28:29], v[90:91], s[22:23], v[28:29] op_sel_hi:[1,0,1]
	v_pk_fma_f32 v[30:31], v[92:93], s[22:23], v[30:31] op_sel_hi:[1,0,1]
	v_pk_fma_f32 v[4:5], v[90:91], s[24:25], v[4:5] op_sel_hi:[1,0,1]
	v_pk_fma_f32 v[6:7], v[92:93], s[24:25], v[6:7] op_sel_hi:[1,0,1]
	v_pk_fma_f32 v[8:9], v[90:91], s[26:27], v[8:9] op_sel_hi:[1,0,1]
	v_pk_fma_f32 v[10:11], v[92:93], s[26:27], v[10:11] op_sel_hi:[1,0,1]
	v_pk_fma_f32 v[12:13], v[90:91], s[28:29], v[12:13] op_sel_hi:[1,0,1]
	v_pk_fma_f32 v[14:15], v[92:93], s[28:29], v[14:15] op_sel_hi:[1,0,1]
	v_pk_fma_f32 v[16:17], v[90:91], s[30:31], v[16:17] op_sel_hi:[1,0,1]
	v_pk_fma_f32 v[18:19], v[92:93], s[30:31], v[18:19] op_sel_hi:[1,0,1]
	v_pk_fma_f32 v[20:21], v[90:91], s[52:53], v[20:21] op_sel_hi:[1,0,1]
	v_pk_fma_f32 v[22:23], v[92:93], s[52:53], v[22:23] op_sel_hi:[1,0,1]
	v_pk_fma_f32 v[24:25], v[90:91], s[54:55], v[24:25] op_sel_hi:[1,0,1]
	v_pk_fma_f32 v[26:27], v[92:93], s[54:55], v[26:27] op_sel_hi:[1,0,1]
	v_pk_fma_f32 v[0:1], v[90:91], s[56:57], v[0:1] op_sel_hi:[1,0,1]
	v_pk_fma_f32 v[2:3], v[92:93], s[56:57], v[2:3] op_sel_hi:[1,0,1]
	s_waitcnt vmcnt(6)
; DI float silu_f(float x) { return x * __builtin_amdgcn_rcpf(1.f + __expf(-x)); }
; DI void phase0(const float* cvec, const float* ada_w, const float* w_in, const float* w_out, bf16* WIN, bf16* WOUT, float* MODP, float* KMAX, bf16* WDT,
;                LAS unsigned char* lds, int tid, int G) {
;     ...
; #pragma unroll 4
;         for (int kk = 0; kk < 16; ++kk) { const int k = k0 + kk; const f32x4 w = __builtin_nontemporal_load((const f32x4*)(W + (size_t)k * 3072 + col));
; #pragma unroll
;             for (int b = 0; b < 8; ++b) { const float ca = silu_f(cvec[b * 1024 + k]); acc[b] += w * ca; } }
	v_readlane_b32 s22, v48, 9
	v_readlane_b32 s24, v48, 25
	v_readlane_b32 s26, v48, 41
	v_readlane_b32 s28, v48, 57
	v_readlane_b32 s30, v49, 9
	v_readlane_b32 s52, v49, 25
	v_readlane_b32 s54, v49, 41
	v_readlane_b32 s56, v49, 57
	v_pk_fma_f32 v[28:29], v[94:95], s[22:23], v[28:29] op_sel_hi:[1,0,1]
	v_pk_fma_f32 v[30:31], v[96:97], s[22:23], v[30:31] op_sel_hi:[1,0,1]
	v_pk_fma_f32 v[4:5], v[94:95], s[24:25], v[4:5] op_sel_hi:[1,0,1]
	v_pk_fma_f32 v[6:7], v[96:97], s[24:25], v[6:7] op_sel_hi:[1,0,1]
	v_pk_fma_f32 v[8:9], v[94:95], s[26:27], v[8:9] op_sel_hi:[1,0,1]
	v_pk_fma_f32 v[10:11], v[96:97], s[26:27], v[10:11] op_sel_hi:[1,0,1]
	v_pk_fma_f32 v[12:13], v[94:95], s[28:29], v[12:13] op_sel_hi:[1,0,1]
	v_pk_fma_f32 v[14:15], v[96:97], s[28:29], v[14:15] op_sel_hi:[1,0,1]
	v_pk_fma_f32 v[16:17], v[94:95], s[30:31], v[16:17] op_sel_hi:[1,0,1]
	v_pk_fma_f32 v[18:19], v[96:97], s[30:31], v[18:19] op_sel_hi:[1,0,1]
	v_pk_fma_f32 v[20:21], v[94:95], s[52:53], v[20:21] op_sel_hi:[1,0,1]
	v_pk_fma_f32 v[22:23], v[96:97], s[52:53], v[22:23] op_sel_hi:[1,0,1]
	v_pk_fma_f32 v[24:25], v[94:95], s[54:55], v[24:25] op_sel_hi:[1,0,1]
	v_pk_fma_f32 v[26:27], v[96:97], s[54:55], v[26:27] op_sel_hi:[1,0,1]
	v_pk_fma_f32 v[0:1], v[94:95], s[56:57], v[0:1] op_sel_hi:[1,0,1]
	v_pk_fma_f32 v[2:3], v[96:97], s[56:57], v[2:3] op_sel_hi:[1,0,1]
	s_waitcnt vmcnt(5)
	v_readlane_b32 s22, v48, 10
	v_readlane_b32 s24, v48, 26
	v_readlane_b32 s26, v48, 42
	v_readlane_b32 s28, v48, 58
	v_readlane_b32 s30, v49, 10
	v_readlane_b32 s52, v49, 26
	v_readlane_b32 s54, v49, 42
	v_readlane_b32 s56, v49, 58
	v_pk_fma_f32 v[28:29], v[98:99], s[22:23], v[28:29] op_sel_hi:[1,0,1]
	v_pk_fma_f32 v[30:31], v[100:101], s[22:23], v[30:31] op_sel_hi:[1,0,1]
	v_pk_fma_f32 v[4:5], v[98:99], s[24:25], v[4:5] op_sel_hi:[1,0,1]
	v_pk_fma_f32 v[6:7], v[100:101], s[24:25], v[6:7] op_sel_hi:[1,0,1]
	v_pk_fma_f32 v[8:9], v[98:99], s[26:27], v[8:9] op_sel_hi:[1,0,1]
	v_pk_fma_f32 v[10:11], v[100:101], s[26:27], v[10:11] op_sel_hi:[1,0,1]
	v_pk_fma_f32 v[12:13], v[98:99], s[28:29], v[12:13] op_sel_hi:[1,0,1]
	v_pk_fma_f32 v[14:15], v[100:101], s[28:29], v[14:15] op_sel_hi:[1,0,1]
	v_pk_fma_f32 v[16:17], v[98:99], s[30:31], v[16:17] op_sel_hi:[1,0,1]
	v_pk_fma_f32 v[18:19], v[100:101], s[30:31], v[18:19] op_sel_hi:[1,0,1]
	v_pk_fma_f32 v[20:21], v[98:99], s[52:53], v[20:21] op_sel_hi:[1,0,1]
	v_pk_fma_f32 v[22:23], v[100:101], s[52:53], v[22:23] op_sel_hi:[1,0,1]
	v_pk_fma_f32 v[24:25], v[98:99], s[54:55], v[24:25] op_sel_hi:[1,0,1]
	v_pk_fma_f32 v[26:27], v[100:101], s[54:55], v[26:27] op_sel_hi:[1,0,1]
	v_pk_fma_f32 v[0:1], v[98:99], s[56:57], v[0:1] op_sel_hi:[1,0,1]
	v_pk_fma_f32 v[2:3], v[100:101], s[56:57], v[2:3] op_sel_hi:[1,0,1]
	s_waitcnt vmcnt(4)
	v_readlane_b32 s22, v48, 11
	v_readlane_b32 s24, v48, 27
	v_readlane_b32 s26, v48, 43
	v_readlane_b32 s28, v48, 59
	v_readlane_b32 s30, v49, 11
	v_readlane_b32 s52, v49, 27
	v_readlane_b32 s54, v49, 43
	v_readlane_b32 s56, v49, 59
	v_pk_fma_f32 v[28:29], v[102:103], s[22:23], v[28:29] op_sel_hi:[1,0,1]
	v_pk_fma_f32 v[30:31], v[104:105], s[22:23], v[30:31] op_sel_hi:[1,0,1]
	v_pk_fma_f32 v[4:5], v[102:103], s[24:25], v[4:5] op_sel_hi:[1,0,1]
	v_pk_fma_f32 v[6:7], v[104:105], s[24:25], v[6:7] op_sel_hi:[1,0,1]
	v_pk_fma_f32 v[8:9], v[102:103], s[26:27], v[8:9] op_sel_hi:[1,0,1]
	v_pk_fma_f32 v[10:11], v[104:105], s[26:27], v[10:11] op_sel_hi:[1,0,1]
	v_pk_fma_f32 v[12:13], v[102:103], s[28:29], v[12:13] op_sel_hi:[1,0,1]
	v_pk_fma_f32 v[14:15], v[104:105], s[28:29], v[14:15] op_sel_hi:[1,0,1]
	v_pk_fma_f32 v[16:17], v[102:103], s[30:31], v[16:17] op_sel_hi:[1,0,1]
	v_pk_fma_f32 v[18:19], v[104:105], s[30:31], v[18:19] op_sel_hi:[1,0,1]
	v_pk_fma_f32 v[20:21], v[102:103], s[52:53], v[20:21] op_sel_hi:[1,0,1]
	v_pk_fma_f32 v[22:23], v[104:105], s[52:53], v[22:23] op_sel_hi:[1,0,1]
	v_pk_fma_f32 v[24:25], v[102:103], s[54:55], v[24:25] op_sel_hi:[1,0,1]
	v_pk_fma_f32 v[26:27], v[104:105], s[54:55], v[26:27] op_sel_hi:[1,0,1]
	v_pk_fma_f32 v[0:1], v[102:103], s[56:57], v[0:1] op_sel_hi:[1,0,1]
	v_pk_fma_f32 v[2:3], v[104:105], s[56:57], v[2:3] op_sel_hi:[1,0,1]
	s_waitcnt vmcnt(3)
	v_readlane_b32 s22, v48, 12
	v_readlane_b32 s24, v48, 28
	v_readlane_b32 s26, v48, 44
	v_readlane_b32 s28, v48, 60
	v_readlane_b32 s30, v49, 12
	v_readlane_b32 s52, v49, 28
	v_readlane_b32 s54, v49, 44
	v_readlane_b32 s56, v49, 60
	v_pk_fma_f32 v[28:29], v[106:107], s[22:23], v[28:29] op_sel_hi:[1,0,1]
	v_pk_fma_f32 v[30:31], v[108:109], s[22:23], v[30:31] op_sel_hi:[1,0,1]
	v_pk_fma_f32 v[4:5], v[106:107], s[24:25], v[4:5] op_sel_hi:[1,0,1]
	v_pk_fma_f32 v[6:7], v[108:109], s[24:25], v[6:7] op_sel_hi:[1,0,1]
	v_pk_fma_f32 v[8:9], v[106:107], s[26:27], v[8:9] op_sel_hi:[1,0,1]
	v_pk_fma_f32 v[10:11], v[108:109], s[26:27], v[10:11] op_sel_hi:[1,0,1]
	v_pk_fma_f32 v[12:13], v[106:107], s[28:29], v[12:13] op_sel_hi:[1,0,1]
	v_pk_fma_f32 v[14:15], v[108:109], s[28:29], v[14:15] op_sel_hi:[1,0,1]
	v_pk_fma_f32 v[16:17], v[106:107], s[30:31], v[16:17] op_sel_hi:[1,0,1]
	v_pk_fma_f32 v[18:19], v[108:109], s[30:31], v[18:19] op_sel_hi:[1,0,1]
	v_pk_fma_f32 v[20:21], v[106:107], s[52:53], v[20:21] op_sel_hi:[1,0,1]
	v_pk_fma_f32 v[22:23], v[108:109], s[52:53], v[22:23] op_sel_hi:[1,0,1]
	v_pk_fma_f32 v[24:25], v[106:107], s[54:55], v[24:25] op_sel_hi:[1,0,1]
	v_pk_fma_f32 v[26:27], v[108:109], s[54:55], v[26:27] op_sel_hi:[1,0,1]
	v_pk_fma_f32 v[0:1], v[106:107], s[56:57], v[0:1] op_sel_hi:[1,0,1]
	v_pk_fma_f32 v[2:3], v[108:109], s[56:57], v[2:3] op_sel_hi:[1,0,1]
	s_waitcnt vmcnt(2)
; #define LAS __attribute__((address_space(3)))
; DI float silu_f(float x) { return x * __builtin_amdgcn_rcpf(1.f + __expf(-x)); }
; DI void phase0(const float* cvec, const float* ada_w, const float* w_in, const float* w_out, bf16* WIN, bf16* WOUT, float* MODP, float* KMAX, bf16* WDT,
;                LAS unsigned char* lds, int tid, int G) {
;     ...
; #pragma unroll 4
;         for (int kk = 0; kk < 16; ++kk) { const int k = k0 + kk; const f32x4 w = __builtin_nontemporal_load((const f32x4*)(W + (size_t)k * 3072 + col));
; #pragma unroll
;             for (int b = 0; b < 8; ++b) { const float ca = silu_f(cvec[b * 1024 + k]); acc[b] += w * ca; } }
;         LAS float* red = (LAS float*)lds;
; #pragma unroll
;         for (int b = 0; b < 8; ++b) *(LAS f32x4*)(red + (wave * 8 + b) * 256 + lane * 4) = acc[b];
;         __syncthreads();
;         { const int idx = tid * 4, b = idx >> 8, cc = idx & 255; f32x4 s = (f32x4){0.f, 0.f, 0.f, 0.f};
; #pragma unroll
;           for (int w = 0; w < 8; ++w) s += *(const LAS f32x4*)(red + (w * 8 + b) * 256 + cc);
;           *(f32x4*)(MODP + ((size_t)(l * 8 + ks) * 8 + b) * 3072 + cgp * 256 + cc) = s; }
;         __syncthreads();
	v_readlane_b32 s22, v48, 13
	v_readlane_b32 s24, v48, 29
	v_readlane_b32 s26, v48, 45
	v_readlane_b32 s28, v48, 61
	v_readlane_b32 s30, v49, 13
	v_readlane_b32 s52, v49, 29
	v_readlane_b32 s54, v49, 45
	v_readlane_b32 s56, v49, 61
	v_pk_fma_f32 v[28:29], v[110:111], s[22:23], v[28:29] op_sel_hi:[1,0,1]
	v_pk_fma_f32 v[30:31], v[112:113], s[22:23], v[30:31] op_sel_hi:[1,0,1]
	v_pk_fma_f32 v[4:5], v[110:111], s[24:25], v[4:5] op_sel_hi:[1,0,1]
	v_pk_fma_f32 v[6:7], v[112:113], s[24:25], v[6:7] op_sel_hi:[1,0,1]
	v_pk_fma_f32 v[8:9], v[110:111], s[26:27], v[8:9] op_sel_hi:[1,0,1]
	v_pk_fma_f32 v[10:11], v[112:113], s[26:27], v[10:11] op_sel_hi:[1,0,1]
	v_pk_fma_f32 v[12:13], v[110:111], s[28:29], v[12:13] op_sel_hi:[1,0,1]
	v_pk_fma_f32 v[14:15], v[112:113], s[28:29], v[14:15] op_sel_hi:[1,0,1]
	v_pk_fma_f32 v[16:17], v[110:111], s[30:31], v[16:17] op_sel_hi:[1,0,1]
	v_pk_fma_f32 v[18:19], v[112:113], s[30:31], v[18:19] op_sel_hi:[1,0,1]
	v_pk_fma_f32 v[20:21], v[110:111], s[52:53], v[20:21] op_sel_hi:[1,0,1]
	v_pk_fma_f32 v[22:23], v[112:113], s[52:53], v[22:23] op_sel_hi:[1,0,1]
	v_pk_fma_f32 v[24:25], v[110:111], s[54:55], v[24:25] op_sel_hi:[1,0,1]
	v_pk_fma_f32 v[26:27], v[112:113], s[54:55], v[26:27] op_sel_hi:[1,0,1]
	v_pk_fma_f32 v[0:1], v[110:111], s[56:57], v[0:1] op_sel_hi:[1,0,1]
	v_pk_fma_f32 v[2:3], v[112:113], s[56:57], v[2:3] op_sel_hi:[1,0,1]
	s_waitcnt vmcnt(1)
	v_readlane_b32 s22, v48, 14
	v_readlane_b32 s24, v48, 30
	v_readlane_b32 s26, v48, 46
	v_readlane_b32 s28, v48, 62
	v_readlane_b32 s30, v49, 14
	v_readlane_b32 s52, v49, 30
	v_readlane_b32 s54, v49, 46
	v_readlane_b32 s56, v49, 62
	v_pk_fma_f32 v[28:29], v[114:115], s[22:23], v[28:29] op_sel_hi:[1,0,1]
	v_pk_fma_f32 v[30:31], v[116:117], s[22:23], v[30:31] op_sel_hi:[1,0,1]
	v_pk_fma_f32 v[4:5], v[114:115], s[24:25], v[4:5] op_sel_hi:[1,0,1]
	v_pk_fma_f32 v[6:7], v[116:117], s[24:25], v[6:7] op_sel_hi:[1,0,1]
	v_pk_fma_f32 v[8:9], v[114:115], s[26:27], v[8:9] op_sel_hi:[1,0,1]
	v_pk_fma_f32 v[10:11], v[116:117], s[26:27], v[10:11] op_sel_hi:[1,0,1]
	v_pk_fma_f32 v[12:13], v[114:115], s[28:29], v[12:13] op_sel_hi:[1,0,1]
	v_pk_fma_f32 v[14:15], v[116:117], s[28:29], v[14:15] op_sel_hi:[1,0,1]
	v_pk_fma_f32 v[16:17], v[114:115], s[30:31], v[16:17] op_sel_hi:[1,0,1]
	v_pk_fma_f32 v[18:19], v[116:117], s[30:31], v[18:19] op_sel_hi:[1,0,1]
	v_pk_fma_f32 v[20:21], v[114:115], s[52:53], v[20:21] op_sel_hi:[1,0,1]
	v_pk_fma_f32 v[22:23], v[116:117], s[52:53], v[22:23] op_sel_hi:[1,0,1]
	v_pk_fma_f32 v[24:25], v[114:115], s[54:55], v[24:25] op_sel_hi:[1,0,1]
	v_pk_fma_f32 v[26:27], v[116:117], s[54:55], v[26:27] op_sel_hi:[1,0,1]
	v_pk_fma_f32 v[0:1], v[114:115], s[56:57], v[0:1] op_sel_hi:[1,0,1]
	v_pk_fma_f32 v[2:3], v[116:117], s[56:57], v[2:3] op_sel_hi:[1,0,1]
	s_waitcnt vmcnt(0)
	v_readlane_b32 s22, v48, 15
	v_readlane_b32 s24, v48, 31
	v_readlane_b32 s26, v48, 47
	v_readlane_b32 s28, v48, 63
	v_readlane_b32 s30, v49, 15
	v_readlane_b32 s52, v49, 31
	v_readlane_b32 s54, v49, 47
	v_readlane_b32 s56, v49, 63
	v_pk_fma_f32 v[28:29], v[118:119], s[22:23], v[28:29] op_sel_hi:[1,0,1]
	v_pk_fma_f32 v[30:31], v[120:121], s[22:23], v[30:31] op_sel_hi:[1,0,1]
	v_pk_fma_f32 v[4:5], v[118:119], s[24:25], v[4:5] op_sel_hi:[1,0,1]
	v_pk_fma_f32 v[6:7], v[120:121], s[24:25], v[6:7] op_sel_hi:[1,0,1]
	v_pk_fma_f32 v[8:9], v[118:119], s[26:27], v[8:9] op_sel_hi:[1,0,1]
	v_pk_fma_f32 v[10:11], v[120:121], s[26:27], v[10:11] op_sel_hi:[1,0,1]
	v_pk_fma_f32 v[12:13], v[118:119], s[28:29], v[12:13] op_sel_hi:[1,0,1]
	v_pk_fma_f32 v[14:15], v[120:121], s[28:29], v[14:15] op_sel_hi:[1,0,1]
	v_pk_fma_f32 v[16:17], v[118:119], s[30:31], v[16:17] op_sel_hi:[1,0,1]
	v_pk_fma_f32 v[18:19], v[120:121], s[30:31], v[18:19] op_sel_hi:[1,0,1]
	v_pk_fma_f32 v[20:21], v[118:119], s[52:53], v[20:21] op_sel_hi:[1,0,1]
	v_pk_fma_f32 v[22:23], v[120:121], s[52:53], v[22:23] op_sel_hi:[1,0,1]
	v_pk_fma_f32 v[24:25], v[118:119], s[54:55], v[24:25] op_sel_hi:[1,0,1]
	v_pk_fma_f32 v[26:27], v[120:121], s[54:55], v[26:27] op_sel_hi:[1,0,1]
	v_pk_fma_f32 v[0:1], v[118:119], s[56:57], v[0:1] op_sel_hi:[1,0,1]
	v_pk_fma_f32 v[2:3], v[120:121], s[56:57], v[2:3] op_sel_hi:[1,0,1]
	ds_write_b128 v54, v[28:31]
	ds_write_b128 v54, v[4:7] offset:1024
	ds_write_b128 v54, v[8:11] offset:2048
	ds_write_b128 v54, v[12:15] offset:3072
	ds_write_b128 v54, v[16:19] offset:4096
	ds_write_b128 v54, v[20:23] offset:5120
	ds_write_b128 v54, v[24:27] offset:6144
	ds_write_b128 v54, v[0:3] offset:7168
	s_waitcnt lgkmcnt(0)
	s_barrier
	ds_read_b128 v[0:3], v55
	ds_read_b128 v[4:7], v55 offset:8192
	ds_read_b128 v[8:11], v55 offset:16384
	s_lshl_b32 s9, s9, 3
	s_or_b32 s10, s9, s21
	s_waitcnt lgkmcnt(2)
	v_pk_add_f32 v[2:3], v[2:3], 0 op_sel_hi:[1,0]
	v_pk_add_f32 v[12:13], v[0:1], 0 op_sel_hi:[1,0]
	s_waitcnt lgkmcnt(1)
	v_pk_add_f32 v[6:7], v[2:3], v[6:7]
	ds_read_b128 v[0:3], v55 offset:24576
	v_pk_add_f32 v[12:13], v[12:13], v[4:5]
	s_waitcnt lgkmcnt(1)
	v_pk_add_f32 v[10:11], v[6:7], v[10:11]
	ds_read_b128 v[4:7], v55 offset:32768
	v_pk_add_f32 v[8:9], v[12:13], v[8:9]
	s_waitcnt lgkmcnt(1)
	v_pk_add_f32 v[10:11], v[10:11], v[2:3]
	v_pk_add_f32 v[12:13], v[8:9], v[0:1]
	ds_read_b128 v[0:3], v55 offset:40960
	s_waitcnt lgkmcnt(1)
	v_pk_add_f32 v[14:15], v[10:11], v[6:7]
	ds_read_b128 v[6:9], v55 offset:49152
	v_pk_add_f32 v[4:5], v[12:13], v[4:5]
	ds_read_b128 v[10:13], v55 offset:57344
	s_waitcnt lgkmcnt(2)
	v_pk_add_f32 v[0:1], v[4:5], v[0:1]
	s_ashr_i32 s11, s10, 31
	s_waitcnt lgkmcnt(1)
	v_pk_add_f32 v[0:1], v[0:1], v[6:7]
	v_lshl_add_u64 v[4:5], s[10:11], 3, v[36:37]
	v_mov_b64_e32 v[6:7], s[58:59]
	v_mad_u64_u32 v[6:7], s[10:11], v4, s12, v[6:7]
	v_pk_add_f32 v[2:3], v[14:15], v[2:3]
	v_mad_i32_i24 v7, v5, s12, v7
	s_ashr_i32 s9, s8, 31
	v_pk_add_f32 v[2:3], v[2:3], v[8:9]
	v_lshl_add_u64 v[4:5], s[8:9], 2, v[6:7]
	s_add_i32 s20, s20, s88
	s_waitcnt lgkmcnt(0)
	v_pk_add_f32 v[2:3], v[2:3], v[12:13]
	v_pk_add_f32 v[0:1], v[0:1], v[10:11]
	v_lshl_add_u64 v[4:5], v[4:5], 0, v[38:39]
	s_cmpk_gt_i32 s20, 0xbf
	global_store_dwordx4 v[4:5], v[0:3], off
	s_barrier
	s_cbranch_scc0 .LBB0_40
